# first grid barrier: the 16 per-XCD census loads issued together (one wait) instead of 15 dependent round trips
# speedup vs baseline: 1.0109x; 1.0109x over previous
.LBB0_584:
	v_readlane_b32 s2, v254, 28
	v_readlane_b32 s3, v254, 29
	s_mov_b64 s[6:7], -1
	s_waitcnt lgkmcnt(0)
	s_nop 4
	global_load_dword v0, v177, s[2:3] sc1
	global_load_dword v1, v177, s[2:3] offset:256 sc1
	global_load_dword v2, v177, s[2:3] offset:512 sc1
	global_load_dword v3, v177, s[2:3] offset:768 sc1
	global_load_dword v4, v177, s[2:3] offset:1024 sc1
	global_load_dword v5, v177, s[2:3] offset:1280 sc1
	global_load_dword v6, v177, s[2:3] offset:1536 sc1
	global_load_dword v7, v177, s[2:3] offset:1792 sc1
	global_load_dword v8, v177, s[2:3] offset:2048 sc1
	global_load_dword v9, v177, s[2:3] offset:2304 sc1
	global_load_dword v10, v177, s[2:3] offset:2560 sc1
	global_load_dword v11, v177, s[2:3] offset:2816 sc1
	global_load_dword v12, v177, s[2:3] offset:3072 sc1
	global_load_dword v13, v177, s[2:3] offset:3328 sc1
	global_load_dword v14, v177, s[2:3] offset:3584 sc1
	global_load_dword v15, v177, s[2:3] offset:3840 sc1
	s_mov_b64 s[2:3], -1
	s_waitcnt vmcnt(0)
	v_add_u32_e32 v16, v1, v0
	v_add_u32_e32 v16, v16, v2
	v_add_u32_e32 v16, v16, v3
	v_add_u32_e32 v16, v16, v4
	v_add_u32_e32 v16, v16, v5
	v_add_u32_e32 v16, v16, v6
	v_add_u32_e32 v16, v16, v7
	v_add_u32_e32 v16, v16, v8
	v_add_u32_e32 v16, v16, v9
	v_add_u32_e32 v16, v16, v10
	v_add_u32_e32 v16, v16, v11
	v_add_u32_e32 v16, v16, v12
	v_add_u32_e32 v16, v16, v13
	v_add_u32_e32 v16, v16, v14
	v_add_u32_e32 v16, v16, v15
	v_cmp_eq_u32_e32 vcc, s66, v16
	s_cbranch_vccnz .LBB0_583
	s_and_b32 s2, s10, 0xff
	s_cmp_eq_u32 s2, 0
	s_mov_b64 s[2:3], -1
	s_mov_b64 s[8:9], -1
	s_sleep 1
	s_cbranch_scc1 .LBB0_588
	s_and_b64 vcc, exec, s[8:9]
	s_cbranch_vccz .LBB0_583
